# gates->merge grid barrier replaced by XCD-local barrier + B-finalize-done counter (Y stores write-through; flag-based dataflow sync)
# baseline (speedup 1.0000x reference)
.LBB0_601:
	s_add_i32 s28, s28, 1
	s_cmp_eq_u32 s28, 2
	s_cbranch_scc0 .Lbfa_skip
	s_cmp_eq_u32 s16, 0
	s_cbranch_scc0 .Lbfa_skip
	v_readlane_b32 s42, v253, 24
	v_readlane_b32 s43, v253, 25
	v_readlane_b32 s39, v252, 23
	s_mov_b64 s[44:45], exec
	s_mov_b64 exec, 1
	s_cmp_lg_u32 s39, 0
	s_cselect_b32 s39, 64, 0x140
	v_mov_b32_e32 v1, s39
	v_mov_b32_e32 v0, 1
	s_nop 4
	global_atomic_add v1, v0, s[42:43]
	s_mov_b64 exec, s[44:45]
.Lbfa_skip:
	s_mul_i32 s5, s28, s98
	s_mul_hi_u32 s4, s28, s98
	s_add_u32 s14, s5, s52
	s_addc_u32 s15, s4, 0
	v_cmp_gt_u64_e64 s[4:5], s[14:15], v[200:201]
	s_and_b64 vcc, exec, s[4:5]
	s_cbranch_vccnz .LBB0_603
	s_and_b32 s6, s14, 7
	s_lshr_b32 s7, s14, 3
	s_mulk_i32 s6, 0x60
	s_add_i32 s6, s6, s7
	s_and_b32 s7, s6, 0xffff
	s_mul_i32 s7, s7, 0xaaab
	s_lshr_b32 s7, s7, 22
	s_lshl_b32 s8, s7, 3
	s_mulk_i32 s7, 0x60
	s_sub_i32 s6, s6, s7
	s_and_b32 s7, s6, 7
	s_or_b32 s7, s7, s8
	s_and_b32 s30, s7, 0x1fff
	s_bfe_u32 s29, s6, 0xd0003
	s_lshr_b32 s8, s6, 3
	s_lshl_b32 s6, s7, 19
	s_add_u32 s6, s17, s6
	s_addc_u32 s7, s18, 0
	s_lshl_b32 s8, s8, 19
	s_add_u32 s8, s19, s8
	s_addc_u32 s9, s20, 0

.LBB0_656:
	s_or_b64 exec, exec, s[8:9]
	s_and_saveexec_b64 s[6:7], s[10:11]
	s_cbranch_execz .LBB0_658
	global_atomic_add v[0:1], v221, off
	s_branch .LBB0_658
.Lbfw:
	v_readlane_b32 s3, v252, 23
	s_nop 3
	s_cmp_lg_u32 s3, 0
	s_cselect_b32 s3, 64, 0x140
	s_add_u32 s8, s4, s3
	s_addc_u32 s9, s5, 0
	s_mov_b32 s3, 0
.Lbfw_loop:
	global_load_dword v0, v195, s[8:9] sc1
	s_waitcnt vmcnt(0)
	v_readfirstlane_b32 s10, v0
	s_nop 3
	s_cmpk_ge_u32 s10, 0x100
	s_cbranch_scc1 .LBB0_658
	s_sleep 1
	s_add_i32 s3, s3, 1
	s_cmp_lt_u32 s3, 0x100000
	s_cbranch_scc1 .Lbfw_loop
